# BE1: attention loop back edge rotated out of the softmax section head (loop control + taken branch before the closing barrier), on top of Y2
# speedup vs baseline: 1.0026x; 1.0019x over previous
.LBB0_628:
	v_and_b32_e32 v5, 0x3fffffc0, v4
	s_add_i32 s8, 0, 0x18000
	v_lshl_add_u32 v171, v5, 2, s8
	s_add_i32 s8, 0, 0xc000
	s_cmp_lg_u32 s8, -1
	v_and_b32_e32 v169, 63, v4
	v_lshlrev_b32_e32 v4, 4, v4
	s_cselect_b32 s8, s8, 0
	v_and_b32_e32 v4, 0x70, v4
	v_lshl_add_u32 v7, v165, 8, s8
	v_or_b32_e32 v8, 32, v168
	v_xad_u32 v175, v8, v4, v7
	v_or_b32_e32 v8, 64, v168
	v_lshlrev_b32_e32 v5, 4, v169
	v_xad_u32 v176, v8, v4, v7
	v_or_b32_e32 v8, 0x60, v168
	s_mov_b32 s48, 2
	s_mov_b32 s49, 1
	v_lshlrev_b32_e32 v6, 1, v169
	s_mov_b32 s52, 0
	v_xad_u32 v174, v168, v4, v7
	v_xad_u32 v177, v8, v4, v7
	v_lshlrev_b32_e32 v66, 3, v169
	s_movk_i32 s50, 0xc0
	v_and_b32_e32 v67, 0xc0, v5
	v_and_b32_e32 v148, 32, v6
	ds_read_b128 v[4:7], v174 offset:0
	ds_read_b128 v[8:11], v174 offset:0x2000
	ds_read_b128 v[12:15], v175 offset:0
	ds_read_b128 v[42:45], v175 offset:0x2000
	ds_read_b128 v[46:49], v176 offset:0
	ds_read_b128 v[50:53], v176 offset:0x2000
	ds_read_b128 v[54:57], v177 offset:0
	ds_read_b128 v[58:61], v177 offset:0x2000
	s_waitcnt lgkmcnt(4)
	s_nop 0
	v_mfma_f32_32x32x16_bf16 v[84:99], v[4:7], v[128:131], 0
	s_mov_b32 s53, s52
	s_mov_b32 s54, s52
	s_mov_b32 s55, s52
	s_mov_b32 s56, s52
	s_mov_b32 s57, s52
	s_mov_b32 s58, s52
	s_mov_b32 s59, s52
	v_mfma_f32_32x32x16_bf16 v[68:83], v[8:11], v[128:131], 0
	s_mov_b32 s60, s52
	s_mov_b32 s61, s52
	s_mov_b32 s62, s52
	s_mov_b32 s63, s52
	s_mov_b32 s64, s52
	s_mov_b32 s65, s52
	s_mov_b32 s66, s52
	v_mfma_f32_32x32x16_bf16 v[84:99], v[12:15], v[124:127], v[84:99]
	s_mov_b32 s67, s52
	v_mov_b64_e32 v[4:5], s[52:53]
	v_mov_b64_e32 v[6:7], s[54:55]
	v_mov_b64_e32 v[8:9], s[56:57]
	v_mov_b64_e32 v[10:11], s[58:59]
	v_mov_b64_e32 v[12:13], s[60:61]
	v_mov_b64_e32 v[14:15], s[62:63]
	v_mfma_f32_32x32x16_bf16 v[68:83], v[42:45], v[124:127], v[68:83]
	v_mov_b64_e32 v[16:17], s[64:65]
	v_mov_b64_e32 v[18:19], s[66:67]
	ds_read_b128 v[42:45], v174 offset:0x80
	ds_read_b128 v[62:65], v174 offset:0x2080
	ds_read_b128 v[132:135], v175 offset:0x80
	ds_read_b128 v[136:139], v175 offset:0x2080
	s_waitcnt lgkmcnt(4)
	v_mfma_f32_32x32x16_bf16 v[84:99], v[46:49], v[120:123], v[84:99]
	v_mfma_f32_32x32x16_bf16 v[68:83], v[50:53], v[120:123], v[68:83]
	v_mfma_f32_32x32x16_bf16 v[84:99], v[54:57], v[116:119], v[84:99]
	v_mfma_f32_32x32x16_bf16 v[68:83], v[58:61], v[116:119], v[68:83]
	ds_read_b128 v[46:49], v176 offset:0x80
	ds_read_b128 v[50:53], v176 offset:0x2080
	ds_read_b128 v[54:57], v177 offset:0x80
	ds_read_b128 v[58:61], v177 offset:0x2080
	s_waitcnt lgkmcnt(4)
	v_mfma_f32_32x32x16_bf16 v[84:99], v[42:45], v[112:115], v[84:99]
	v_mfma_f32_32x32x16_bf16 v[68:83], v[62:65], v[112:115], v[68:83]
	v_mfma_f32_32x32x16_bf16 v[84:99], v[132:135], v[108:111], v[84:99]
	v_mfma_f32_32x32x16_bf16 v[68:83], v[136:139], v[108:111], v[68:83]
	s_waitcnt lgkmcnt(0)
	v_mfma_f32_32x32x16_bf16 v[84:99], v[46:49], v[104:107], v[84:99]
	v_mfma_f32_32x32x16_bf16 v[68:83], v[50:53], v[104:107], v[68:83]
	v_mfma_f32_32x32x16_bf16 v[84:99], v[54:57], v[100:103], v[84:99]
	v_mfma_f32_32x32x16_bf16 v[68:83], v[58:61], v[100:103], v[68:83]
	s_add_i32 s8, 0, 0x10000
	s_waitcnt vmcnt(0)
	s_waitcnt vmcnt(3)
	ds_write_b128 v40, v[20:23] offset:16384
	s_waitcnt vmcnt(2)
	ds_write_b128 v41, v[24:27] offset:16384
	v_add_u32_e32 v20, s8, v180
	s_waitcnt vmcnt(1)
	ds_write_b128 v20, v[28:31]
	v_add_u32_e32 v20, s8, v181
	s_waitcnt vmcnt(0)
	ds_write_b128 v20, v[32:35]
	v_add_co_u32_e32 v20, vcc, s22, v38
	s_nop 1
	v_addc_co_u32_e32 v21, vcc, 0, v39, vcc
	global_load_dwordx4 v[132:135], v[20:21], off
	v_add_co_u32_e32 v20, vcc, s24, v38
	s_nop 1
	v_addc_co_u32_e32 v21, vcc, 0, v39, vcc
	global_load_dwordx4 v[140:143], v[20:21], off
	v_add_co_u32_e32 v20, vcc, s22, v36
	s_nop 1
	v_addc_co_u32_e32 v21, vcc, 0, v37, vcc
	global_load_dwordx4 v[136:139], v[20:21], off
	v_add_co_u32_e32 v20, vcc, s24, v36
	s_nop 1
	v_addc_co_u32_e32 v21, vcc, 0, v37, vcc
	global_load_dwordx4 v[144:147], v[20:21], off
	s_waitcnt lgkmcnt(0)
	s_barrier
	s_movk_i32 s8, 0x118
	s_cmp_lg_u32 0, -1
	v_and_or_b32 v20, v66, s8, v148
	s_cselect_b32 s8, 0, 0
	v_add3_u32 v173, v67, s8, v20
	v_mov_b64_e32 v[66:67], v[18:19]
	v_mov_b64_e32 v[50:51], v[18:19]
	v_mov_b64_e32 v[34:35], v[18:19]
	v_cmp_gt_u32_e64 s[38:39], 32, v169
	v_lshl_add_u32 v172, v165, 2, v171
	v_mov_b32_e32 v183, 0
	v_mov_b32_e32 v182, 0xf149f2ca
	v_mov_b64_e32 v[64:65], v[16:17]
	v_mov_b64_e32 v[62:63], v[14:15]
	v_mov_b64_e32 v[60:61], v[12:13]
	v_mov_b64_e32 v[58:59], v[10:11]
	v_mov_b64_e32 v[56:57], v[8:9]
	v_mov_b64_e32 v[54:55], v[6:7]
	v_mov_b64_e32 v[52:53], v[4:5]
	v_mov_b64_e32 v[48:49], v[16:17]
	v_mov_b64_e32 v[46:47], v[14:15]
	v_mov_b64_e32 v[44:45], v[12:13]
	v_mov_b64_e32 v[42:43], v[10:11]
	v_mov_b64_e32 v[40:41], v[8:9]
	v_mov_b64_e32 v[38:39], v[6:7]
	v_mov_b64_e32 v[36:37], v[4:5]
	v_mov_b64_e32 v[32:33], v[16:17]
	v_mov_b64_e32 v[30:31], v[14:15]
	v_mov_b64_e32 v[28:29], v[12:13]
	v_mov_b64_e32 v[26:27], v[10:11]
	v_mov_b64_e32 v[24:25], v[8:9]
	v_mov_b64_e32 v[22:23], v[6:7]
	v_mov_b64_e32 v[20:21], v[4:5]
	s_mov_b32 s51, 2
	s_branch .LBB0_629
.Lmy_attn_top:
	s_waitcnt lgkmcnt(0)
	s_barrier
	v_fma_f32 v183, v183, v184, v185
.LBB0_629:
	v_max_f32_e32 v148, v84, v85
	v_max_f32_e32 v149, v68, v69
	v_max3_f32 v148, v148, v86, v87
	v_max3_f32 v149, v149, v70, v71
	v_max3_f32 v148, v148, v88, v89
	v_max3_f32 v149, v149, v72, v73
	v_max3_f32 v148, v148, v90, v91
	v_max3_f32 v149, v149, v74, v75
	v_max3_f32 v148, v148, v92, v93
	v_max3_f32 v149, v149, v76, v77
	v_max3_f32 v148, v148, v94, v95
	v_max3_f32 v149, v149, v78, v79
	v_max3_f32 v148, v148, v96, v97
	v_max3_f32 v149, v149, v80, v81
	v_max3_f32 v148, v148, v98, v99
	v_max3_f32 v149, v149, v82, v83
	v_max_f32_e32 v148, v148, v149
	v_mov_b32_e32 v149, v148
	s_nop 1
	v_permlane32_swap_b32_e32 v148, v149
	v_max_f32_e32 v148, v148, v149
	v_sub_f32_e32 v149, v148, v182
	v_cmp_ge_f32_e32 vcc, s23, v149
	v_max_f32_e32 v148, v182, v148
	s_cmp_eq_u64 vcc, exec
	s_cselect_b64 vcc, -1, 0
	v_sub_f32_e32 v150, v182, v148
	v_cndmask_b32_e32 v182, v148, v182, vcc
	v_mul_f32_e32 v148, 0xbe0293ee, v182
	v_fmamk_f32 v84, v84, 0x3e0293ee, v148
	v_fmamk_f32 v85, v85, 0x3e0293ee, v148
	v_fmamk_f32 v86, v86, 0x3e0293ee, v148
	v_fmamk_f32 v87, v87, 0x3e0293ee, v148
	v_fmamk_f32 v88, v88, 0x3e0293ee, v148
	v_fmamk_f32 v89, v89, 0x3e0293ee, v148
	v_fmamk_f32 v90, v90, 0x3e0293ee, v148
	v_fmamk_f32 v91, v91, 0x3e0293ee, v148
	v_fmamk_f32 v92, v92, 0x3e0293ee, v148
	v_fmamk_f32 v93, v93, 0x3e0293ee, v148
	v_fmamk_f32 v94, v94, 0x3e0293ee, v148
	v_fmamk_f32 v95, v95, 0x3e0293ee, v148
	v_fmamk_f32 v96, v96, 0x3e0293ee, v148
	v_fmamk_f32 v97, v97, 0x3e0293ee, v148
	v_fmamk_f32 v98, v98, 0x3e0293ee, v148
	v_fmamk_f32 v99, v99, 0x3e0293ee, v148
	v_fmamk_f32 v68, v68, 0x3e0293ee, v148
	v_fmamk_f32 v69, v69, 0x3e0293ee, v148
	v_fmamk_f32 v70, v70, 0x3e0293ee, v148
	v_fmamk_f32 v71, v71, 0x3e0293ee, v148
	v_fmamk_f32 v72, v72, 0x3e0293ee, v148
	v_fmamk_f32 v73, v73, 0x3e0293ee, v148
	v_fmamk_f32 v74, v74, 0x3e0293ee, v148
	v_fmamk_f32 v75, v75, 0x3e0293ee, v148
	v_fmamk_f32 v76, v76, 0x3e0293ee, v148
	v_fmamk_f32 v77, v77, 0x3e0293ee, v148
	v_fmamk_f32 v78, v78, 0x3e0293ee, v148
	v_fmamk_f32 v79, v79, 0x3e0293ee, v148
	v_fmamk_f32 v80, v80, 0x3e0293ee, v148
	v_fmamk_f32 v81, v81, 0x3e0293ee, v148
	v_fmamk_f32 v82, v82, 0x3e0293ee, v148
	v_fmac_f32_e32 v148, 0x3e0293ee, v83
	v_exp_f32_e32 v83, v84
	v_exp_f32_e32 v84, v85
	v_exp_f32_e32 v85, v86
	v_add_f32_e32 v149, v84, v83
	v_exp_f32_e32 v86, v87
	v_add_f32_e32 v149, v85, v149
	v_exp_f32_e32 v87, v88
	v_add_f32_e32 v149, v86, v149
	v_exp_f32_e32 v88, v89
	v_add_f32_e32 v149, v87, v149
	v_exp_f32_e32 v89, v90
	v_add_f32_e32 v149, v88, v149
	v_exp_f32_e32 v90, v91
	v_add_f32_e32 v149, v89, v149
	v_exp_f32_e32 v91, v92
	v_add_f32_e32 v149, v90, v149
	v_exp_f32_e32 v92, v93
	v_add_f32_e32 v149, v91, v149
	v_exp_f32_e32 v93, v94
	v_add_f32_e32 v149, v92, v149
	v_exp_f32_e32 v94, v95
	v_add_f32_e32 v149, v93, v149
	v_exp_f32_e32 v95, v96
	v_add_f32_e32 v149, v94, v149
	v_exp_f32_e32 v96, v97
	v_add_f32_e32 v149, v95, v149
	v_exp_f32_e32 v97, v98
	v_add_f32_e32 v149, v96, v149
	v_exp_f32_e32 v98, v99
	v_add_f32_e32 v149, v97, v149
	v_exp_f32_e32 v99, v148
	v_add_f32_e32 v149, v98, v149
	v_exp_f32_e32 v68, v68
	v_exp_f32_e32 v69, v69
	v_add_f32_e32 v149, v68, v149
	v_exp_f32_e32 v70, v70
	v_add_f32_e32 v149, v69, v149
	v_exp_f32_e32 v71, v71
	v_add_f32_e32 v149, v70, v149
	v_exp_f32_e32 v72, v72
	v_add_f32_e32 v149, v71, v149
	v_exp_f32_e32 v73, v73
	v_add_f32_e32 v149, v72, v149
	v_exp_f32_e32 v74, v74
	v_add_f32_e32 v149, v73, v149
	v_exp_f32_e32 v75, v75
	v_add_f32_e32 v149, v74, v149
	v_exp_f32_e32 v76, v76
	v_add_f32_e32 v149, v75, v149
	v_exp_f32_e32 v77, v77
	v_add_f32_e32 v149, v76, v149
	v_exp_f32_e32 v78, v78
	v_add_f32_e32 v149, v77, v149
	v_exp_f32_e32 v79, v79
	v_add_f32_e32 v149, v78, v149
	v_exp_f32_e32 v80, v80
	v_add_f32_e32 v149, v79, v149
	v_exp_f32_e32 v81, v81
	v_add_f32_e32 v149, v80, v149
	v_exp_f32_e32 v82, v82
	v_add_f32_e32 v149, v81, v149
	v_mul_f32_e32 v150, 0x3e0293ee, v150
	v_add_f32_e32 v149, v82, v149
	v_exp_f32_e32 v150, v150
	v_add_f32_e32 v185, v99, v149
	v_cndmask_b32_e64 v184, v150, 1.0, vcc
	v_cvt_pk_bf16_f32 v148, v83, v84
	v_cvt_pk_bf16_f32 v149, v85, v86
	v_cvt_pk_bf16_f32 v150, v87, v88
	v_cvt_pk_bf16_f32 v151, v89, v90
	v_cvt_pk_bf16_f32 v152, v91, v92
	v_cvt_pk_bf16_f32 v153, v93, v94
	v_cvt_pk_bf16_f32 v154, v95, v96
	v_cvt_pk_bf16_f32 v155, v97, v98
	v_cvt_pk_bf16_f32 v156, v68, v69
	v_cvt_pk_bf16_f32 v157, v70, v71
	v_cvt_pk_bf16_f32 v158, v72, v73
	v_cvt_pk_bf16_f32 v159, v74, v75
	v_cvt_pk_bf16_f32 v160, v76, v77
	v_cvt_pk_bf16_f32 v161, v78, v79
	v_cvt_pk_bf16_f32 v162, v80, v81
	v_cvt_pk_bf16_f32 v163, v82, v99
	s_mov_b32 s53, s52
	s_cbranch_vccnz .LBB0_633
	s_and_saveexec_b64 s[16:17], s[38:39]
	ds_write_b32 v172, v184 offset:128
	s_or_b64 exec, exec, s[16:17]
	s_waitcnt lgkmcnt(0)
	v_add_u32_e32 v80, v171, v168
	ds_read_b128 v[68:71], v80 offset:224
	ds_read_b128 v[72:75], v80 offset:192
	ds_read_b128 v[76:79], v80 offset:160
	ds_read_b128 v[80:83], v80 offset:128
	s_waitcnt lgkmcnt(3)
	v_pk_mul_f32 v[16:17], v[16:17], v[68:69]
	s_waitcnt lgkmcnt(2)
	v_pk_mul_f32 v[12:13], v[12:13], v[72:73]
	s_waitcnt lgkmcnt(1)
	v_pk_mul_f32 v[8:9], v[8:9], v[76:77]
	v_pk_mul_f32 v[18:19], v[18:19], v[70:71]
	v_pk_mul_f32 v[14:15], v[14:15], v[74:75]
	v_pk_mul_f32 v[10:11], v[10:11], v[78:79]
	s_waitcnt lgkmcnt(0)
	v_pk_mul_f32 v[6:7], v[6:7], v[82:83]
	v_pk_mul_f32 v[4:5], v[4:5], v[80:81]
	v_pk_mul_f32 v[64:65], v[64:65], v[68:69]
	v_pk_mul_f32 v[60:61], v[60:61], v[72:73]
	v_pk_mul_f32 v[56:57], v[56:57], v[76:77]
	v_pk_mul_f32 v[66:67], v[66:67], v[70:71]
	v_pk_mul_f32 v[62:63], v[62:63], v[74:75]
	v_pk_mul_f32 v[58:59], v[58:59], v[78:79]
	v_pk_mul_f32 v[54:55], v[54:55], v[82:83]
	v_pk_mul_f32 v[52:53], v[52:53], v[80:81]
	v_pk_mul_f32 v[48:49], v[48:49], v[68:69]
	v_pk_mul_f32 v[44:45], v[44:45], v[72:73]
	v_pk_mul_f32 v[40:41], v[40:41], v[76:77]
	v_pk_mul_f32 v[50:51], v[50:51], v[70:71]
	v_pk_mul_f32 v[46:47], v[46:47], v[74:75]
	v_pk_mul_f32 v[42:43], v[42:43], v[78:79]
	v_pk_mul_f32 v[38:39], v[38:39], v[82:83]
	v_pk_mul_f32 v[36:37], v[36:37], v[80:81]
	v_pk_mul_f32 v[32:33], v[32:33], v[68:69]
	v_pk_mul_f32 v[28:29], v[28:29], v[72:73]
	v_pk_mul_f32 v[24:25], v[24:25], v[76:77]
	v_pk_mul_f32 v[34:35], v[34:35], v[70:71]
	v_pk_mul_f32 v[30:31], v[30:31], v[74:75]
	v_pk_mul_f32 v[26:27], v[26:27], v[78:79]
	v_pk_mul_f32 v[22:23], v[22:23], v[82:83]
	v_pk_mul_f32 v[20:21], v[20:21], v[80:81]

.LBB0_635:
	s_add_i32 s50, s50, 64
	s_cmp_eq_u32 s46, s48
	s_cbranch_scc1 .Lmy_attn_exit
	s_mov_b32 s52, s49
	s_mov_b32 s49, s51
	s_mov_b32 s51, s53
	s_branch .Lmy_attn_top
.Lmy_attn_exit:
	s_waitcnt lgkmcnt(0)
	s_barrier
	v_fma_f32 v183, v183, v184, v185
.LBB0_637:
	v_mov_b32_e32 v148, v183
	v_mov_b32_e32 v186, v183
	s_nop 1
	v_permlane32_swap_b32_e32 v148, v186
	v_add_f32_e32 v148, v148, v186
	v_max_f32_e32 v2, v85, v85
	s_waitcnt vmcnt(0)
	v_max_f32_e32 v132, v84, v84
	v_max_f32_e32 v2, v132, v2
	v_max3_f32 v2, v2, v86, v87
	v_max3_f32 v2, v2, v88, v89
	v_max3_f32 v2, v2, v90, v91
	v_max3_f32 v2, v2, v92, v93
	v_max3_f32 v2, v2, v94, v95
	v_max3_f32 v2, v2, v96, v97
	v_max3_f32 v2, v2, v98, v99
	v_max3_f32 v2, v2, v68, v69
	v_max3_f32 v2, v2, v70, v71
	v_max3_f32 v2, v2, v72, v73
	v_max3_f32 v2, v2, v74, v75
	v_max3_f32 v2, v2, v76, v77
	v_max3_f32 v2, v2, v78, v79
	v_max3_f32 v2, v2, v80, v81
	v_max3_f32 v2, v2, v82, v83
	v_mov_b32_e32 v132, v2
	s_nop 1
	v_permlane32_swap_b32_e32 v2, v132
	v_max_f32_e32 v132, v132, v132
	v_max_f32_e32 v2, v2, v2
	v_max_f32_e32 v2, v2, v132
	v_sub_f32_e32 v132, v2, v182
	v_cmp_ge_f32_e32 vcc, s23, v132
	v_max_f32_e32 v133, v182, v182
	s_cmp_eq_u64 vcc, exec
	v_max_f32_e32 v133, v133, v2
	s_cselect_b64 vcc, -1, 0
	v_cndmask_b32_e32 v151, v133, v182, vcc
	v_mul_f32_e32 v132, 0xbe0293ee, v151
	v_fmamk_f32 v84, v84, 0x3e0293ee, v132
	v_fmamk_f32 v85, v85, 0x3e0293ee, v132
	v_fmamk_f32 v86, v86, 0x3e0293ee, v132
	v_fmamk_f32 v87, v87, 0x3e0293ee, v132
	v_fmamk_f32 v88, v88, 0x3e0293ee, v132
	v_fmamk_f32 v89, v89, 0x3e0293ee, v132
	v_fmamk_f32 v90, v90, 0x3e0293ee, v132
	v_fmamk_f32 v91, v91, 0x3e0293ee, v132
	v_fmamk_f32 v92, v92, 0x3e0293ee, v132
	v_fmamk_f32 v93, v93, 0x3e0293ee, v132
	v_fmamk_f32 v94, v94, 0x3e0293ee, v132
	v_fmamk_f32 v95, v95, 0x3e0293ee, v132
	v_fmamk_f32 v96, v96, 0x3e0293ee, v132
	v_fmamk_f32 v97, v97, 0x3e0293ee, v132
	v_fmamk_f32 v98, v98, 0x3e0293ee, v132
	v_fmamk_f32 v99, v99, 0x3e0293ee, v132
	v_fmamk_f32 v68, v68, 0x3e0293ee, v132
	v_fmamk_f32 v69, v69, 0x3e0293ee, v132
	v_fmamk_f32 v70, v70, 0x3e0293ee, v132
	v_fmamk_f32 v71, v71, 0x3e0293ee, v132
	v_fmamk_f32 v72, v72, 0x3e0293ee, v132
	v_fmamk_f32 v73, v73, 0x3e0293ee, v132
	v_fmamk_f32 v74, v74, 0x3e0293ee, v132
	v_fmamk_f32 v75, v75, 0x3e0293ee, v132
	v_fmamk_f32 v76, v76, 0x3e0293ee, v132
	v_fmamk_f32 v77, v77, 0x3e0293ee, v132
	v_fmamk_f32 v78, v78, 0x3e0293ee, v132
	v_fmamk_f32 v79, v79, 0x3e0293ee, v132
	v_fmamk_f32 v80, v80, 0x3e0293ee, v132
	v_fmamk_f32 v81, v81, 0x3e0293ee, v132
	v_fmamk_f32 v82, v82, 0x3e0293ee, v132
	v_fmac_f32_e32 v132, 0x3e0293ee, v83
	v_exp_f32_e32 v83, v84
	v_exp_f32_e32 v84, v85
	v_exp_f32_e32 v85, v86
	v_exp_f32_e32 v86, v87
	v_exp_f32_e32 v87, v88
	v_exp_f32_e32 v88, v89
	v_exp_f32_e32 v89, v90
	v_exp_f32_e32 v90, v91
	v_exp_f32_e32 v91, v92
	v_exp_f32_e32 v92, v93
	v_exp_f32_e32 v93, v94
	v_exp_f32_e32 v94, v95
	v_exp_f32_e32 v95, v96
	v_exp_f32_e32 v96, v97
	v_exp_f32_e32 v97, v98
	v_exp_f32_e32 v98, v99
	v_exp_f32_e32 v99, v132
	v_add_f32_e32 v132, 0, v83
	v_add_f32_e32 v132, v84, v132
	v_add_f32_e32 v132, v85, v132
	v_add_f32_e32 v132, v86, v132
	v_add_f32_e32 v132, v87, v132
	v_add_f32_e32 v132, v88, v132
	v_add_f32_e32 v132, v89, v132
	v_add_f32_e32 v132, v90, v132
	v_add_f32_e32 v132, v91, v132
	v_add_f32_e32 v132, v92, v132
	v_add_f32_e32 v132, v93, v132
	v_add_f32_e32 v132, v94, v132
	v_exp_f32_e32 v68, v68
	v_add_f32_e32 v132, v95, v132
	v_exp_f32_e32 v69, v69
	v_add_f32_e32 v132, v96, v132
	v_exp_f32_e32 v70, v70
	v_add_f32_e32 v132, v97, v132
	v_exp_f32_e32 v71, v71
	v_add_f32_e32 v132, v98, v132
	v_exp_f32_e32 v72, v72
	v_add_f32_e32 v132, v68, v132
	v_exp_f32_e32 v73, v73
	v_add_f32_e32 v132, v69, v132
	v_exp_f32_e32 v74, v74
	v_add_f32_e32 v132, v70, v132
	v_exp_f32_e32 v75, v75
	v_add_f32_e32 v132, v71, v132
	v_exp_f32_e32 v76, v76
	v_add_f32_e32 v132, v72, v132
	v_exp_f32_e32 v77, v77
	v_add_f32_e32 v132, v73, v132
	v_exp_f32_e32 v78, v78
	v_add_f32_e32 v132, v74, v132
	v_exp_f32_e32 v79, v79
	v_add_f32_e32 v132, v75, v132
	v_exp_f32_e32 v80, v80
	v_add_f32_e32 v132, v76, v132
	v_exp_f32_e32 v81, v81
	v_add_f32_e32 v132, v77, v132
	v_sub_f32_e32 v2, v182, v133
	v_exp_f32_e32 v82, v82
	v_add_f32_e32 v132, v78, v132
	v_mul_f32_e32 v2, 0x3e0293ee, v2
	v_add_f32_e32 v132, v79, v132
	v_exp_f32_e32 v2, v2
	v_add_f32_e32 v132, v80, v132
	v_add_f32_e32 v132, v81, v132
	v_add_f32_e32 v132, v82, v132
	v_add_f32_e32 v149, v99, v132
	v_cndmask_b32_e64 v2, v2, 1.0, vcc
	v_mov_b32_e32 v150, v149
	v_cvt_pk_bf16_f32 v132, v83, v84
	v_cvt_pk_bf16_f32 v133, v85, v86
	v_cvt_pk_bf16_f32 v134, v87, v88
	v_cvt_pk_bf16_f32 v135, v89, v90
	v_cvt_pk_bf16_f32 v136, v91, v92
	v_cvt_pk_bf16_f32 v137, v93, v94
	v_cvt_pk_bf16_f32 v138, v95, v96
	v_cvt_pk_bf16_f32 v139, v97, v98
	v_cvt_pk_bf16_f32 v140, v68, v69
	v_cvt_pk_bf16_f32 v141, v70, v71
	v_cvt_pk_bf16_f32 v142, v72, v73
	v_cvt_pk_bf16_f32 v143, v74, v75
	v_cvt_pk_bf16_f32 v144, v76, v77
	v_cvt_pk_bf16_f32 v145, v78, v79
	v_cvt_pk_bf16_f32 v146, v80, v81
	v_cvt_pk_bf16_f32 v147, v82, v99
	s_nop 1
	v_permlane32_swap_b32_e32 v149, v150
	v_cmp_gt_f32_e32 vcc, 1.0, v2
	s_cbranch_vccz .LBB0_641
	s_and_saveexec_b64 s[16:17], s[38:39]
	ds_write_b32 v172, v2 offset:128
	s_or_b64 exec, exec, s[16:17]
	s_waitcnt lgkmcnt(0)
	v_add_u32_e32 v80, v171, v168
	ds_read_b128 v[68:71], v80 offset:224
	ds_read_b128 v[72:75], v80 offset:192
	ds_read_b128 v[76:79], v80 offset:160
	ds_read_b128 v[80:83], v80 offset:128
	s_waitcnt lgkmcnt(3)
	v_pk_mul_f32 v[16:17], v[16:17], v[68:69]
	s_waitcnt lgkmcnt(2)
	v_pk_mul_f32 v[12:13], v[12:13], v[72:73]
	s_waitcnt lgkmcnt(1)
	v_pk_mul_f32 v[8:9], v[8:9], v[76:77]
	v_pk_mul_f32 v[18:19], v[18:19], v[70:71]
	v_pk_mul_f32 v[14:15], v[14:15], v[74:75]
	v_pk_mul_f32 v[10:11], v[10:11], v[78:79]
	s_waitcnt lgkmcnt(0)
	v_pk_mul_f32 v[6:7], v[6:7], v[82:83]
	v_pk_mul_f32 v[4:5], v[4:5], v[80:81]
	v_pk_mul_f32 v[64:65], v[64:65], v[68:69]
	v_pk_mul_f32 v[60:61], v[60:61], v[72:73]
	v_pk_mul_f32 v[56:57], v[56:57], v[76:77]
	v_pk_mul_f32 v[66:67], v[66:67], v[70:71]
	v_pk_mul_f32 v[62:63], v[62:63], v[74:75]
	v_pk_mul_f32 v[58:59], v[58:59], v[78:79]
	v_pk_mul_f32 v[54:55], v[54:55], v[82:83]
	v_pk_mul_f32 v[52:53], v[52:53], v[80:81]
	v_pk_mul_f32 v[48:49], v[48:49], v[68:69]
	v_pk_mul_f32 v[44:45], v[44:45], v[72:73]
	v_pk_mul_f32 v[40:41], v[40:41], v[76:77]
	v_pk_mul_f32 v[50:51], v[50:51], v[70:71]
	v_pk_mul_f32 v[46:47], v[46:47], v[74:75]
	v_pk_mul_f32 v[42:43], v[42:43], v[78:79]
	v_pk_mul_f32 v[38:39], v[38:39], v[82:83]
	v_pk_mul_f32 v[36:37], v[36:37], v[80:81]
	v_pk_mul_f32 v[32:33], v[32:33], v[68:69]
	v_pk_mul_f32 v[28:29], v[28:29], v[72:73]
	v_pk_mul_f32 v[24:25], v[24:25], v[76:77]
	v_pk_mul_f32 v[34:35], v[34:35], v[70:71]
	v_pk_mul_f32 v[30:31], v[30:31], v[74:75]
	v_pk_mul_f32 v[26:27], v[26:27], v[78:79]
	v_pk_mul_f32 v[22:23], v[22:23], v[82:83]
	v_pk_mul_f32 v[20:21], v[20:21], v[80:81]
